# sidewait vmcnt(16) + INB WGM=4 + INB parked stores (6 per wave trickled into next K-loop) + ATTB table rebuild skipped when head unchanged
# speedup vs baseline: 1.0074x; 1.0074x over previous
; __device__ __forceinline__ float wave_sum(float v) { v += dpp_mov<0xB1>(v); v += dpp_mov<0x4E>(v); v += dpp_mov<0x141>(v); v += dpp_mov<0x140>(v); v = sum_x16(v); return sum_x32(v); }
; __device__ __forceinline__ void st16_wt(void* p, u32x4 v) { if (WT_STORES) asm volatile("global_store_dwordx4 %0, %1, off sc1\n\ts_nop 1" :: "v"(p), "v"(v) : "memory"); else *(u32x4*)p = v; }
;     __device__ __forceinline__ void side_finish(const Side& s, int lane) const {
;         if (MODE == 0 && s.row < xrows) {
;             float q = 0.f;
; #pragma unroll
;             for (int j = 0; j < 4; ++j) q += (s.v[j][0] * s.v[j][0] + s.v[j][1] * s.v[j][1]) + (s.v[j][2] * s.v[j][2] + s.v[j][3] * s.v[j][3]);
;             const float rstd = __builtin_amdgcn_rsqf(wave_sum(q) * (1.0f / 1024.0f) + 1e-6f);
;             const bool odd = lane & 1;
;             bf16_t* orow = xd + (size_t)s.row * 1024 + 4 * (lane & ~1);
; #pragma unroll
;             for (int jp = 0; jp < 2; ++jp) {
;                 const int ja = 2 * jp, jb = 2 * jp + 1;
;                 const unsigned pax = cvt_pk_bf16(s.v[ja][0] * rstd, s.v[ja][1] * rstd), pay = cvt_pk_bf16(s.v[ja][2] * rstd, s.v[ja][3] * rstd);
;                 const unsigned pbx = cvt_pk_bf16(s.v[jb][0] * rstd, s.v[jb][1] * rstd), pby = cvt_pk_bf16(s.v[jb][2] * rstd, s.v[jb][3] * rstd);
;                 const unsigned rx = (unsigned)__builtin_amdgcn_update_dpp(0, (int)(odd ? pax : pbx), 0xB1, 0xF, 0xF, true), ry = (unsigned)__builtin_amdgcn_update_dpp(0, (int)(odd ? pay : pby), 0xB1, 0xF, 0xF, true);
;                 u32x4 w; w.x = odd ? rx : pax; w.y = odd ? ry : pay; w.z = odd ? pbx : rx; w.w = odd ? pby : ry;
;                 *(u32x4*)(orow + (odd ? 256 * jb : 256 * ja)) = w;
;             }
;         }
;     __device__ __forceinline__ void operator()(const f32x4 (&acc)[2][2][4][2], const Unit& u, int wr, int wc, int fr, int fq, const bool reuse, PG8_LAS float* rscr, PG8_LAS const float* gains) const {
;     ...
;                 bf16_t* p = p0 + (size_t)(8 * ai + m) * step16;
; #pragma unroll
;                 for (int bj = 0; bj < 2; ++bj) { u32x4 w; w.x = cvt_pk_bf16(v[bj][0][0], v[bj][0][1]); w.y = cvt_pk_bf16(v[bj][0][2], v[bj][0][3]); w.z = cvt_pk_bf16(v[bj][1][0], v[bj][1][1]); w.w = cvt_pk_bf16(v[bj][1][2], v[bj][1][3]);
;                     st16_wt(p + 32 * bj, w); }
.LBB0_246:
	s_nop 0
	v_lshl_add_u64 v[32:33], v[48:49], 0, s[88:89]
	s_andn2_b64 vcc, exec, s[80:81]
	v_cvt_pk_bf16_f32 v20, v20, v21
	v_cvt_pk_bf16_f32 v21, v22, v23
	v_cvt_pk_bf16_f32 v22, v16, v17
	v_cvt_pk_bf16_f32 v23, v18, v19
	global_store_dwordx4 v[32:33], v[20:23], off
	v_cvt_pk_bf16_f32 v16, v24, v25
	v_cvt_pk_bf16_f32 v17, v26, v27
	v_cvt_pk_bf16_f32 v18, v28, v29
	v_cvt_pk_bf16_f32 v19, v30, v31
	global_store_dwordx4 v[32:33], v[16:19], off offset:64
	s_cbranch_vccnz .LBB0_248
	s_waitcnt vmcnt(16)
	v_mul_f32_e32 v16, v13, v13
	v_mul_f32_e32 v17, v15, v15
	v_fmac_f32_e32 v16, v12, v12
	v_fmac_f32_e32 v17, v14, v14
	v_add_f32_e32 v16, v16, v17
	v_mul_f32_e32 v17, v9, v9
	v_mul_f32_e32 v18, v11, v11
	v_fmac_f32_e32 v17, v8, v8
	v_fmac_f32_e32 v18, v10, v10
	v_add_f32_e32 v17, v17, v18
	v_add_f32_e32 v16, v17, v16
	v_mul_f32_e32 v17, v5, v5
	v_mul_f32_e32 v18, v7, v7
	v_fmac_f32_e32 v17, v4, v4
	v_fmac_f32_e32 v18, v6, v6
	v_add_f32_e32 v17, v17, v18
	v_add_f32_e32 v16, v17, v16
	v_mul_f32_e32 v17, v1, v1
	v_mul_f32_e32 v18, v3, v3
	v_fmac_f32_e32 v17, v0, v0
	v_fmac_f32_e32 v18, v2, v2
	v_add_f32_e32 v17, v17, v18
	v_add_f32_e32 v16, v17, v16
	s_ashr_i32 s77, s76, 31
	s_lshl_b64 s[12:13], s[76:77], 11
	v_add_f32_dpp v16, v16, v16 quad_perm:[1,0,3,2] row_mask:0xf bank_mask:0xf bound_ctrl:1
	v_lshl_add_u64 v[20:21], v[176:177], 0, s[12:13]
	v_mov_b32_e32 v183, v161
	v_add_f32_dpp v16, v16, v16 quad_perm:[2,3,0,1] row_mask:0xf bank_mask:0xf bound_ctrl:1
	v_mov_b32_e32 v185, v161
	s_nop 0
	v_add_f32_dpp v16, v16, v16 row_half_mirror row_mask:0xf bank_mask:0xf bound_ctrl:1
	s_nop 1
	v_add_f32_dpp v16, v16, v16 row_mirror row_mask:0xf bank_mask:0xf bound_ctrl:1
	v_mov_b32_e32 v17, v16
	s_nop 1
	v_permlane16_swap_b32_e32 v16, v17
	v_add_f32_e32 v16, v16, v17
	v_mov_b32_e32 v17, v16
	s_nop 1
	v_permlane32_swap_b32_e32 v16, v17
	v_add_f32_e32 v16, v16, v17
	v_fmamk_f32 v16, v16, 0x3a800000, v190
	v_rsq_f32_e32 v24, v16
	s_nop 0
	v_mul_f32_e32 v16, v12, v24
	v_mul_f32_e32 v17, v13, v24
	v_cvt_pk_bf16_f32 v16, v16, v17
	v_mul_f32_e32 v17, v14, v24
	v_mul_f32_e32 v18, v15, v24
	v_cvt_pk_bf16_f32 v17, v17, v18
	v_mul_f32_e32 v18, v8, v24
	v_mul_f32_e32 v19, v9, v24
	v_cvt_pk_bf16_f32 v18, v18, v19
	v_mul_f32_e32 v19, v10, v24
	v_mul_f32_e32 v22, v11, v24
	v_cvt_pk_bf16_f32 v19, v19, v22
	v_cndmask_b32_e64 v22, v16, v18, s[34:35]
	v_cndmask_b32_e64 v23, v17, v19, s[34:35]
	s_nop 0
	v_mov_b32_dpp v22, v22 quad_perm:[1,0,3,2] row_mask:0xf bank_mask:0xf bound_ctrl:1
	v_mov_b32_dpp v23, v23 quad_perm:[1,0,3,2] row_mask:0xf bank_mask:0xf bound_ctrl:1
	v_cndmask_b32_e64 v16, v22, v16, s[34:35]
	v_cndmask_b32_e64 v17, v23, v17, s[34:35]
	v_cndmask_b32_e64 v18, v18, v22, s[34:35]
	v_cndmask_b32_e64 v19, v19, v23, s[34:35]
	v_lshl_add_u64 v[22:23], v[20:21], 0, v[182:183]
	global_store_dwordx4 v[22:23], v[16:19], off
	v_mul_f32_e32 v22, v3, v24
	v_lshl_add_u64 v[20:21], v[20:21], 0, v[184:185]
	v_mul_f32_e32 v16, v4, v24
	v_mul_f32_e32 v17, v5, v24
	v_cvt_pk_bf16_f32 v16, v16, v17
	v_mul_f32_e32 v17, v6, v24
	v_mul_f32_e32 v18, v7, v24
	v_cvt_pk_bf16_f32 v17, v17, v18
	v_mul_f32_e32 v18, v0, v24
	v_mul_f32_e32 v19, v1, v24
	v_cvt_pk_bf16_f32 v18, v18, v19
	v_mul_f32_e32 v19, v2, v24
	v_cvt_pk_bf16_f32 v19, v19, v22
	v_cndmask_b32_e64 v22, v16, v18, s[34:35]
	v_cndmask_b32_e64 v23, v17, v19, s[34:35]
	s_nop 0
	v_mov_b32_dpp v22, v22 quad_perm:[1,0,3,2] row_mask:0xf bank_mask:0xf bound_ctrl:1
	v_mov_b32_dpp v23, v23 quad_perm:[1,0,3,2] row_mask:0xf bank_mask:0xf bound_ctrl:1
	v_cndmask_b32_e64 v16, v22, v16, s[34:35]
	v_cndmask_b32_e64 v17, v23, v17, s[34:35]
	v_cndmask_b32_e64 v18, v18, v22, s[34:35]
	v_cndmask_b32_e64 v19, v19, v23, s[34:35]
	global_store_dwordx4 v[20:21], v[16:19], off

;     __host__ __device__ bool next(int i, Unit& u) const {
;         const long L = (long)i * G + c; if (L >= nwg) return false;
;         int wgid = (int)L; { const int q = nwg / NXCD, r = nwg % NXCD, xcd = wgid % NXCD, off = wgid / NXCD; wgid = (xcd < r ? xcd * (q + 1) : r * (q + 1) + (xcd - r) * q) + off; }
;         const int nig = WGM * nN, gid = wgid / nig, fm = gid * WGM, gsz = (nM - fm) < WGM ? (nM - fm) : WGM;
;         u.pm = fm + ((wgid % nig) % gsz); u.pn = (wgid % nig) / gsz; return true;
;     }
.LBB0_509:
	s_cmp_lt_i32 s66, 11
	s_cselect_b64 s[6:7], -1, 0
	s_and_b64 s[6:7], s[6:7], s[0:1]
	s_add_u32 s33, s70, 0xa400000
	s_addc_u32 s40, s71, 0
	s_add_u32 s0, s70, 0x16400000
	s_addc_u32 s1, s71, 0
	s_andn2_b64 vcc, exec, s[6:7]
	s_cbranch_vccnz .LBB0_628
	s_cmpk_lt_i32 s87, 0x800
	v_mbcnt_lo_u32_b32 v120, -1, 0
	v_mbcnt_hi_u32_b32 v120, -1, v120
	s_cselect_b64 s[8:9], -1, 0
	v_add_u32_e32 v112, s65, v120
	s_cmpk_gt_i32 s87, 0x7ff
	v_readfirstlane_b32 s2, v112
	s_cbranch_scc1 .LBB0_513
	v_readlane_b32 s6, v252, 2
	s_lshl_b32 s10, s58, 8
	v_readlane_b32 s7, v252, 3
	s_mul_i32 s11, s58, 0x101
	s_and_b64 s[6:7], s[6:7], exec
	s_cselect_b32 s6, s11, s10
	v_readlane_b32 s7, v252, 5
	s_add_i32 s6, s6, s7
	s_ashr_i32 s7, s6, 31
	s_lshr_b32 s7, s7, 26
	s_add_i32 s7, s6, s7
	s_ashr_i32 s10, s7, 6
	s_and_b32 s7, s7, 0xffc0
	s_sub_i32 s6, s6, s7
	s_bfe_i32 s7, s6, 0x80000
	s_bfe_u32 s7, s7, 0x3000c
	s_add_i32 s7, s6, s7
	s_bfe_i32 s11, s7, 0x80000
	s_and_b32 s7, s7, 0xfc
	s_sub_i32 s6, s6, s7
	s_lshl_b32 s10, s10, 2
	s_sext_i32_i16 s11, s11
	s_sext_i32_i8 s6, s6
	s_add_i32 s6, s10, s6
	s_ashr_i32 s12, s11, 2
	s_andn2_b64 vcc, exec, s[8:9]
	s_cbranch_vccz .LBB0_514

; #define PG8_LAS __attribute__((address_space(3)))
;     __device__ __forceinline__ void stage_consts(PG8_LAS float* gl, int tid) const { if (tid < 2 * NGQ) gl[tid] = (tid < NGQ) ? qg[tid] * qscale : kg[tid - NGQ]; }
; #define PG8_WAIT_V(n) asm volatile("s_waitcnt vmcnt(" #n ")" ::: "memory")
; #define PG8_BAR __builtin_amdgcn_s_barrier()
;     int lane_; asm volatile("v_mbcnt_lo_u32_b32 %0, -1, 0\n\tv_mbcnt_hi_u32_b32 %0, -1, %0" : "=v"(lane_)); const int tid_ = wave_ * 64 + lane_;
;     const int tid = tid_, wid = __builtin_amdgcn_readfirstlane(tid >> 6), lane = tid & 63, wr = wid >> 2, wc = wid & 3, fr = lane & 15, fq = lane >> 4;
;     const int K = g.K, nt = K / BK;
;     unsigned voffA[2], voffB[2];
; #pragma unroll
;     for (int i = 0; i < 2; ++i) { int R, C; stage_rc(tid * 16 + i * 8192, R, C);
;         const int Rb = Epi::HEADMAP ? (64 * (R >> 5) + perm32(R & 31)) : R;
;         voffA[i] = (unsigned)(R * K + C) * 2u; voffB[i] = (unsigned)(Rb * K + C) * 2u; }
;     const size_t kstep = (size_t)(BK * 2);
;     const size_t hstep = (size_t)HALF * K * 2;
;     const size_t hstepB = Epi::HEADMAP ? (size_t)32 * K * 2 : hstep;
;     const size_t tstep = 2 * hstep;
;     const unsigned ldsw = (unsigned)wid * 1024u;
;     const int aoff = lds_byte(wr * 64 + fr, fq * 8), boff = lds_byte(wc * 32 + fr, fq * 8);
;     ...
;     Unit cur, nxt; int ui = 0; int prev_pm = -1;
;     if (!S.next(0, cur)) return;
;     f32x4 acc[2][2][4][2];
; #pragma unroll
;     for (int a = 0; a < 2; ++a)
; #pragma unroll
;         for (int b = 0; b < 2; ++b)
; #pragma unroll
;             for (int m = 0; m < 4; ++m)
; #pragma unroll
;                 for (int n = 0; n < 2; ++n) PG8_ZERO4(acc[a][b][m][n]);
;     bf16x8 At[4][2], B0[2][2], B1[2][2];
;     const char* cA = (const char*)g.A + (size_t)cur.pm * tstep; const char* cB = (const char*)g.Bt + (size_t)cur.pn * tstep;
;     PG8_STAGE(PG8_SB(0, 0), cB, voffB); PG8_STAGE(PG8_SB(0, 1), cB + hstepB, voffB); PG8_STAGE(PG8_SA(0, 0), cA, voffA); PG8_STAGE(PG8_SA(0, 1), cA + hstep, voffA);
;     E.stage_consts((PG8_LAS float*)(lds + 131072) + 1024, tid);
;     if (wr == 1) PG8_BAR;
;     PG8_WAIT_V(2); PG8_BAR;
;     PG8_STAGE(PG8_SB(1, 0), cB + kstep, voffB); PG8_STAGE(PG8_SA(1, 0), cA + kstep, voffA); PG8_STAGE(PG8_SB(1, 1), cB + hstepB + kstep, voffB);
;     PG8_WAIT_V(6); PG8_BAR;
.LBB0_522:
	s_mov_b64 s[10:11], 0x80
	s_and_b32 s44, s16, 3
	s_add_i32 m0, s29, 0x18000
	v_lshl_add_u64 v[118:119], v[118:119], 0, s[10:11]
	s_lshl_b32 s45, s7, 6
	s_lshl_b32 s7, s7, 13
	s_lshl_b32 s13, s44, 12
	s_waitcnt vmcnt(2)
	s_barrier
	global_load_lds_dwordx4 v[118:119], off
	v_lshl_add_u64 v[116:117], v[116:117], 0, s[10:11]
	s_add_i32 m0, s29, 0x1a000
	s_add_i32 s48, s29, 0x8000
	s_add_i32 s49, s29, 0xa000
	global_load_lds_dwordx4 v[116:117], off
	v_lshl_add_u64 v[114:115], v[114:115], 0, s[10:11]
	s_mov_b32 m0, s48
	s_add_u32 s14, s22, 0x10080
	global_load_lds_dwordx4 v[114:115], off
	v_lshl_add_u64 v[112:113], v[112:113], 0, s[10:11]
	s_mov_b32 m0, s49
	s_addc_u32 s15, s23, 0
	global_load_lds_dwordx4 v[112:113], off
	s_add_i32 m0, s29, 0x1c000
	v_lshl_add_u64 v[112:113], s[14:15], 0, v[174:175]
	global_load_lds_dwordx4 v[112:113], off
	v_lshl_add_u64 v[112:113], s[14:15], 0, v[178:179]
	s_add_i32 m0, s29, 0x1e000
	v_and_b32_e32 v196, 15, v120
	global_load_lds_dwordx4 v[112:113], off
	v_bfe_u32 v113, v120, 4, 2
	v_lshlrev_b32_e32 v180, 4, v113
	v_lshlrev_b32_e32 v115, 2, v196
	v_lshl_or_b32 v114, v196, 6, v180
	v_and_b32_e32 v116, 32, v115
	v_bitop3_b32 v117, v114, s7, v116 bitop3:0xde
	s_add_i32 s7, 0, 0x20000
	s_cmpk_lt_u32 s2, 0x100
	s_cselect_b64 s[14:15], -1, 0
	s_add_i32 s2, 0, 0x21000
	v_lshlrev_b32_e32 v112, 3, v113
	v_lshl_add_u32 v199, v113, 5, s2
	v_cmp_eq_u32_e64 s[34:35], 0, v113
	v_lshlrev_b32_e32 v113, 14, v121
	v_and_b32_e32 v113, 0xffff8000, v113
	v_bitop3_b32 v197, v114, s13, v116 bitop3:0xde
	v_lshl_add_u32 v113, v122, 11, v113
	v_and_b32_e32 v114, 1, v121
	v_lshl_or_b32 v113, v114, 6, v113
	v_lshl_add_u32 v184, v123, 1, v113
	v_lshlrev_b32_e32 v113, 14, v124
	v_and_b32_e32 v113, 0xffff8000, v113
	s_waitcnt vmcnt(6)
	v_lshl_add_u32 v113, v125, 11, v113
	v_and_b32_e32 v114, 1, v124
	s_lshl_b32 s2, s44, 6
	v_mov_b32_e32 v181, 0
	v_lshl_or_b32 v113, v114, 6, v113
	s_mov_b32 s13, 0
	v_add_u32_e32 v198, s7, v115
	s_lshl_b32 s50, s16, 9
	v_lshl_add_u64 v[182:183], s[4:5], 0, v[180:181]
	v_mov_b32_e32 v185, v181
	v_lshl_add_u32 v186, v126, 1, v113
	v_mov_b32_e32 v187, v181
	s_mov_b32 s38, -1
	v_mov_b64_e32 v[188:189], 0x800
	v_mov_b64_e32 v[190:191], 0x7ff
	s_add_i32 s51, 0, 0x10000
	s_add_i32 s52, 0, 0x14000
	v_add_u32_e32 v200, 0, v117
	s_lshl_b32 s4, s2, 1
	v_mov_b32_e32 v201, 0x358637bd
	v_lshlrev_b32_e32 v180, 1, v112
	s_mov_b32 s53, 0
	s_mov_b32 s101, 0
	s_barrier
	s_branch .LBB0_525

;     __host__ __device__ bool next(int i, Unit& u) const {
;         const long L = (long)i * G + c; if (L >= nwg) return false;
;         int wgid = (int)L; { const int q = nwg / NXCD, r = nwg % NXCD, xcd = wgid % NXCD, off = wgid / NXCD; wgid = (xcd < r ? xcd * (q + 1) : r * (q + 1) + (xcd - r) * q) + off; }
;         const int nig = WGM * nN, gid = wgid / nig, fm = gid * WGM, gsz = (nM - fm) < WGM ? (nM - fm) : WGM;
;         u.pm = fm + ((wgid % nig) % gsz); u.pn = (wgid % nig) / gsz; return true;
;     }
.LBB0_530:
	s_ashr_i32 s2, s2, 3
	s_add_i32 s2, s16, s2
	s_ashr_i32 s5, s2, 31
	s_lshr_b32 s5, s5, 26
	s_add_i32 s5, s2, s5
	s_ashr_i32 s6, s5, 6
	s_lshl_b32 s6, s6, 2
	s_sub_i32 s7, 0x80, s6
	s_min_i32 s7, s7, 4
	s_abs_i32 s16, s7
	s_waitcnt lgkmcnt(0)
	v_cvt_f32_u32_e32 v112, s16
	s_sub_i32 s18, 0, s16
	s_and_b32 s5, s5, 0xffffffc0
	s_sub_i32 s2, s2, s5
	v_rcp_iflag_f32_e32 v112, v112
	s_abs_i32 s5, s2
	s_xor_b32 s17, s2, s7
	s_ashr_i32 s17, s17, 31
	v_mul_f32_e32 v112, 0x4f7ffffe, v112
	v_cvt_u32_f32_e32 v112, v112
	s_nop 0
	v_readfirstlane_b32 s19, v112
	s_mul_i32 s18, s18, s19
	s_mul_hi_u32 s18, s19, s18
	s_add_i32 s19, s19, s18
	s_mul_hi_u32 s18, s5, s19
	s_mul_i32 s19, s18, s16
	s_sub_i32 s5, s5, s19
	s_add_i32 s20, s18, 1
	s_sub_i32 s19, s5, s16
	s_cmp_ge_u32 s5, s16
	s_cselect_b32 s18, s20, s18
	s_cselect_b32 s5, s19, s5
	s_add_i32 s19, s18, 1
	s_cmp_ge_u32 s5, s16
	s_cselect_b32 s5, s19, s18
	s_xor_b32 s5, s5, s17
	s_sub_i32 s16, s5, s17
	s_mul_i32 s5, s16, s7
	s_sub_i32 s2, s2, s5
	s_add_i32 s6, s6, s2

; #define PG8_STAGE(bufoff, gbase, voff) do { _Pragma("unroll") for (int _i = 0; _i < 2; ++_i) \
;         __builtin_amdgcn_global_load_lds((const unsigned*)((const char*)(gbase) + (voff)[_i]), (PG8_LAS unsigned*)(lds + (bufoff) + ldsw + _i * 8192), 16, 0, 0); } while (0)
; #define PG8_LDA(dst, b, h) do { _Pragma("unroll") for (int m = 0; m < 4; ++m) _Pragma("unroll") for (int k = 0; k < 2; ++k) dst[m][k] = *(const PG8_LAS bf16x8*)(lds + PG8_SA(b, h) + aoff + m * 2048 + k * 1024); } while (0)
; #define PG8_LDB(dst, b, h) do { _Pragma("unroll") for (int n = 0; n < 2; ++n) _Pragma("unroll") for (int k = 0; k < 2; ++k) dst[n][k] = *(const PG8_LAS bf16x8*)(lds + PG8_SB(b, h) + boff + n * 2048 + k * 1024); } while (0)
; #define PG8_WAIT_V(n) asm volatile("s_waitcnt vmcnt(" #n ")" ::: "memory")
; #define PG8_WAIT_L(n) asm volatile("s_waitcnt lgkmcnt(" #n ")" ::: "memory")
; #define PG8_BAR __builtin_amdgcn_s_barrier()
; #define PG8_SCHED __builtin_amdgcn_sched_barrier(0)
;     ...
;         for (int t = 0; t < nt; t += 2) {
;             const bool last = (t == nt - 2);
;             const char* a1 = cA + (size_t)(t + 1) * kstep;
;             const char* a2 = last ? nA : cA + (size_t)(t + 2) * kstep; const char* b2 = last ? nB : cB + (size_t)(t + 2) * kstep;
;             const char* a3 = a2 + kstep; const char* b3 = b2 + kstep;
;             PG8_LDB(B0, 0, 0); PG8_LDB(B1, 0, 1); PG8_SCHED; PG8_LDA(At, 0, 0); PG8_STAGE(PG8_SA(1, 1), a1 + hstep, voffA);
;             PG8_WAIT_V(8); PG8_WAIT_L(0); PG8_BAR; PG8_MMA(0, 0, At, B0); PG8_MMA(0, 1, At, B1); PG8_BAR; PG8_SCHED;
;             PG8_LDA(At, 0, 1); PG8_STAGE(PG8_SB(0, 0), b2, voffB); PG8_STAGE(PG8_SB(0, 1), b2 + hstepB, voffB); PG8_STAGE(PG8_SA(0, 0), a2, voffA);
;             PG8_WAIT_V(8); PG8_WAIT_L(0); PG8_BAR; PG8_MMA(1, 0, At, B0); PG8_MMA(1, 1, At, B1); PG8_BAR; PG8_SCHED;
.LBB0_532:
	s_waitcnt lgkmcnt(0)
	v_add_u32_e32 v124, s51, v197
	s_waitcnt lgkmcnt(0)
	v_add_u32_e32 v156, s52, v197
	ds_read_b128 v[112:115], v124
	ds_read_b128 v[116:119], v124 offset:1024
	ds_read_b128 v[120:123], v124 offset:2048
	ds_read_b128 v[124:127], v124 offset:3072
	ds_read_b128 v[144:147], v156
	ds_read_b128 v[148:151], v156 offset:1024
	ds_read_b128 v[152:155], v156 offset:2048
	ds_read_b128 v[156:159], v156 offset:3072
	s_add_u32 s22, s24, 0xfffc0080
	s_addc_u32 s23, s25, -1
	s_cmp_eq_u32 s56, 12
	s_cselect_b32 s27, s2, s23
	s_cselect_b32 s26, s5, s22
	s_cselect_b32 s23, s7, s55
	s_cselect_b32 s22, s17, s39
	v_lshl_add_u64 v[218:219], s[24:25], 0, v[184:185]
	s_add_i32 m0, s29, 0xc000
	ds_read_b128 v[160:163], v200
	ds_read_b128 v[164:167], v200 offset:1024
	ds_read_b128 v[168:171], v200 offset:2048
	ds_read_b128 v[192:195], v200 offset:3072
	ds_read_b128 v[202:205], v200 offset:4096
	ds_read_b128 v[206:209], v200 offset:5120
	ds_read_b128 v[210:213], v200 offset:6144
	ds_read_b128 v[214:217], v200 offset:7168
	global_load_lds_dwordx4 v[218:219], off
	v_lshl_add_u64 v[218:219], s[24:25], 0, v[186:187]
	s_add_i32 m0, s29, 0xe000
	s_nop 0
	global_load_lds_dwordx4 v[218:219], off
	s_cmp_eq_u32 s101, 0
	s_cbranch_scc1 .Lpkb_w8a
	s_cmp_eq_u32 s101, 6
	s_cbranch_scc1 .Lpkb_s0
	s_cmp_eq_u32 s101, 5
	s_cbranch_scc1 .Lpkb_s1
	s_cmp_eq_u32 s101, 4
	s_cbranch_scc1 .Lpkb_s2
	s_cmp_eq_u32 s101, 3
	s_cbranch_scc1 .Lpkb_s3
	s_cmp_eq_u32 s101, 2
	s_cbranch_scc1 .Lpkb_s4
	global_store_dwordx4 v[254:255], v[248:251], off offset:64
	s_branch .Lpkb_w9a
.Lpkb_s0:
	global_store_dwordx4 v[254:255], v[228:231], off
	s_branch .Lpkb_w9a
.Lpkb_s1:
	global_store_dwordx4 v[254:255], v[232:235], off offset:64
	v_add_co_u32_e32 v254, vcc, s100, v254
	s_nop 1
	v_addc_co_u32_e32 v255, vcc, 0, v255, vcc
	s_branch .Lpkb_w9a
.Lpkb_s2:
	global_store_dwordx4 v[254:255], v[236:239], off
	s_branch .Lpkb_w9a
.Lpkb_s3:
	global_store_dwordx4 v[254:255], v[240:243], off offset:64
	v_add_co_u32_e32 v254, vcc, s100, v254
	s_nop 1
	v_addc_co_u32_e32 v255, vcc, 0, v255, vcc
	s_branch .Lpkb_w9a
.Lpkb_s4:
	global_store_dwordx4 v[254:255], v[244:247], off
.Lpkb_w9a:
	s_waitcnt vmcnt(9)
	s_branch .Lpkb_da
.Lpkb_w8a:
	s_waitcnt vmcnt(8)
.Lpkb_da:
	s_waitcnt lgkmcnt(0)
	s_barrier
	s_setprio 1
	s_waitcnt lgkmcnt(0)
	v_mfma_f32_16x16x32_f16 v[132:135], v[112:115], v[160:163], v[132:135]
	v_mfma_f32_16x16x32_f16 v[128:131], v[120:123], v[160:163], v[128:131]
	v_mfma_f32_16x16x32_f16 v[100:103], v[112:115], v[168:171], v[100:103]
	v_mfma_f32_16x16x32_f16 v[96:99], v[120:123], v[168:171], v[96:99]
	v_mfma_f32_16x16x32_f16 v[84:87], v[112:115], v[202:205], v[84:87]
	v_mfma_f32_16x16x32_f16 v[80:83], v[120:123], v[202:205], v[80:83]
	v_mfma_f32_16x16x32_f16 v[68:71], v[112:115], v[210:213], v[68:71]
	v_mfma_f32_16x16x32_f16 v[64:67], v[120:123], v[210:213], v[64:67]
	v_mfma_f32_16x16x32_f16 v[132:135], v[116:119], v[164:167], v[132:135]
	v_mfma_f32_16x16x32_f16 v[128:131], v[124:127], v[164:167], v[128:131]
	v_mfma_f32_16x16x32_f16 v[100:103], v[116:119], v[192:195], v[100:103]
	v_mfma_f32_16x16x32_f16 v[96:99], v[124:127], v[192:195], v[96:99]
	v_mfma_f32_16x16x32_f16 v[84:87], v[116:119], v[206:209], v[84:87]
	v_mfma_f32_16x16x32_f16 v[80:83], v[124:127], v[206:209], v[80:83]
	v_mfma_f32_16x16x32_f16 v[68:71], v[116:119], v[214:217], v[68:71]
	v_mfma_f32_16x16x32_f16 v[64:67], v[124:127], v[214:217], v[64:67]
	s_setprio 0
	s_setprio 1
	v_mfma_f32_16x16x32_f16 v[140:143], v[144:147], v[160:163], v[140:143]
	v_mfma_f32_16x16x32_f16 v[136:139], v[152:155], v[160:163], v[136:139]
	v_mfma_f32_16x16x32_f16 v[108:111], v[144:147], v[168:171], v[108:111]
	v_mfma_f32_16x16x32_f16 v[104:107], v[152:155], v[168:171], v[104:107]
	v_mfma_f32_16x16x32_f16 v[92:95], v[144:147], v[202:205], v[92:95]
	v_mfma_f32_16x16x32_f16 v[88:91], v[152:155], v[202:205], v[88:91]
	v_mfma_f32_16x16x32_f16 v[76:79], v[144:147], v[210:213], v[76:79]
	v_mfma_f32_16x16x32_f16 v[72:75], v[152:155], v[210:213], v[72:75]
	v_mfma_f32_16x16x32_f16 v[140:143], v[148:151], v[164:167], v[140:143]
	v_mfma_f32_16x16x32_f16 v[136:139], v[156:159], v[164:167], v[136:139]
	v_mfma_f32_16x16x32_f16 v[108:111], v[148:151], v[192:195], v[108:111]
	v_mfma_f32_16x16x32_f16 v[104:107], v[156:159], v[192:195], v[104:107]
	v_mfma_f32_16x16x32_f16 v[92:95], v[148:151], v[206:209], v[92:95]
	v_mfma_f32_16x16x32_f16 v[88:91], v[156:159], v[206:209], v[88:91]
	v_mfma_f32_16x16x32_f16 v[76:79], v[148:151], v[214:217], v[76:79]
	v_mfma_f32_16x16x32_f16 v[72:75], v[156:159], v[214:217], v[72:75]
	s_setprio 0
	s_barrier
	s_add_i32 s57, s51, s28
	v_lshl_add_u64 v[218:219], s[22:23], 0, v[174:175]
	s_mov_b32 m0, s57
	ds_read_b128 v[160:163], v200 offset:16384
	ds_read_b128 v[164:167], v200 offset:17408
	ds_read_b128 v[168:171], v200 offset:18432
	ds_read_b128 v[192:195], v200 offset:19456
	ds_read_b128 v[202:205], v200 offset:20480
	ds_read_b128 v[206:209], v200 offset:21504
	ds_read_b128 v[210:213], v200 offset:22528
	ds_read_b128 v[214:217], v200 offset:23552
	global_load_lds_dwordx4 v[218:219], off
	s_add_i32 m0, s57, 0x2000
	s_add_u32 s58, s22, 0x10000
	v_lshl_add_u64 v[220:221], s[22:23], 0, v[178:179]
	s_addc_u32 s59, s23, 0
	s_add_i32 s57, s52, s28
	global_load_lds_dwordx4 v[220:221], off
	v_lshl_add_u64 v[222:223], s[58:59], 0, v[174:175]
	s_mov_b32 m0, s57
	v_lshl_add_u64 v[224:225], s[26:27], 0, v[176:177]
	global_load_lds_dwordx4 v[222:223], off
	v_lshl_add_u64 v[222:223], s[58:59], 0, v[178:179]
	s_add_i32 m0, s57, 0x2000
	s_nop 0
	global_load_lds_dwordx4 v[222:223], off
	v_lshl_add_u64 v[222:223], s[26:27], 0, v[172:173]
	s_mov_b32 m0, s29
	s_nop 0
	global_load_lds_dwordx4 v[222:223], off
	s_mov_b32 m0, s41
	s_nop 0
	global_load_lds_dwordx4 v[224:225], off
	s_cmp_eq_u32 s101, 0
	s_cbranch_scc1 .Lpkb_w8b
	s_waitcnt vmcnt(9)
	s_branch .Lpkb_db

; #define PG8_STAGE(bufoff, gbase, voff) do { _Pragma("unroll") for (int _i = 0; _i < 2; ++_i) \
;         __builtin_amdgcn_global_load_lds((const unsigned*)((const char*)(gbase) + (voff)[_i]), (PG8_LAS unsigned*)(lds + (bufoff) + ldsw + _i * 8192), 16, 0, 0); } while (0)
; #define PG8_LDA(dst, b, h) do { _Pragma("unroll") for (int m = 0; m < 4; ++m) _Pragma("unroll") for (int k = 0; k < 2; ++k) dst[m][k] = *(const PG8_LAS bf16x8*)(lds + PG8_SA(b, h) + aoff + m * 2048 + k * 1024); } while (0)
; #define PG8_LDB(dst, b, h) do { _Pragma("unroll") for (int n = 0; n < 2; ++n) _Pragma("unroll") for (int k = 0; k < 2; ++k) dst[n][k] = *(const PG8_LAS bf16x8*)(lds + PG8_SB(b, h) + boff + n * 2048 + k * 1024); } while (0)
; #define PG8_WAIT_V(n) asm volatile("s_waitcnt vmcnt(" #n ")" ::: "memory")
; #define PG8_WAIT_L(n) asm volatile("s_waitcnt lgkmcnt(" #n ")" ::: "memory")
; #define PG8_BAR __builtin_amdgcn_s_barrier()
; #define PG8_SCHED __builtin_amdgcn_sched_barrier(0)
;     ...
;             PG8_WAIT_V(8); PG8_WAIT_L(0); PG8_BAR; PG8_MMA(1, 0, At, B0); PG8_MMA(1, 1, At, B1); PG8_BAR; PG8_SCHED;
;             PG8_LDB(B0, 1, 0); PG8_LDB(B1, 1, 1); PG8_SCHED; PG8_LDA(At, 1, 0); PG8_STAGE(PG8_SA(0, 1), a2 + hstep, voffA);
;             PG8_WAIT_V(8); PG8_WAIT_L(0); PG8_BAR; PG8_MMA(0, 0, At, B0); PG8_MMA(0, 1, At, B1); PG8_BAR; PG8_SCHED;
.Lpkb_db:
	s_waitcnt lgkmcnt(0)
	s_barrier
	s_setprio 1
	s_waitcnt lgkmcnt(0)
	v_mfma_f32_16x16x32_f16 v[52:55], v[112:115], v[160:163], v[52:55]
	v_mfma_f32_16x16x32_f16 v[48:51], v[120:123], v[160:163], v[48:51]
	v_mfma_f32_16x16x32_f16 v[36:39], v[112:115], v[168:171], v[36:39]
	v_mfma_f32_16x16x32_f16 v[32:35], v[120:123], v[168:171], v[32:35]
	v_mfma_f32_16x16x32_f16 v[20:23], v[112:115], v[202:205], v[20:23]
	v_mfma_f32_16x16x32_f16 v[16:19], v[120:123], v[202:205], v[16:19]
	v_mfma_f32_16x16x32_f16 v[4:7], v[112:115], v[210:213], v[4:7]
	v_mfma_f32_16x16x32_f16 v[0:3], v[120:123], v[210:213], v[0:3]
	v_mfma_f32_16x16x32_f16 v[52:55], v[116:119], v[164:167], v[52:55]
	v_mfma_f32_16x16x32_f16 v[48:51], v[124:127], v[164:167], v[48:51]
	v_mfma_f32_16x16x32_f16 v[36:39], v[116:119], v[192:195], v[36:39]
	v_mfma_f32_16x16x32_f16 v[32:35], v[124:127], v[192:195], v[32:35]
	v_mfma_f32_16x16x32_f16 v[20:23], v[116:119], v[206:209], v[20:23]
	v_mfma_f32_16x16x32_f16 v[16:19], v[124:127], v[206:209], v[16:19]
	v_mfma_f32_16x16x32_f16 v[4:7], v[116:119], v[214:217], v[4:7]
	v_mfma_f32_16x16x32_f16 v[0:3], v[124:127], v[214:217], v[0:3]
	s_setprio 0
	s_setprio 1
	v_mfma_f32_16x16x32_f16 v[60:63], v[144:147], v[160:163], v[60:63]
	v_mfma_f32_16x16x32_f16 v[56:59], v[152:155], v[160:163], v[56:59]
	v_mfma_f32_16x16x32_f16 v[44:47], v[144:147], v[168:171], v[44:47]
	v_mfma_f32_16x16x32_f16 v[40:43], v[152:155], v[168:171], v[40:43]
	v_mfma_f32_16x16x32_f16 v[28:31], v[144:147], v[202:205], v[28:31]
	v_mfma_f32_16x16x32_f16 v[24:27], v[152:155], v[202:205], v[24:27]
	v_mfma_f32_16x16x32_f16 v[12:15], v[144:147], v[210:213], v[12:15]
	v_mfma_f32_16x16x32_f16 v[8:11], v[152:155], v[210:213], v[8:11]
	v_mfma_f32_16x16x32_f16 v[60:63], v[148:151], v[164:167], v[60:63]
	v_mfma_f32_16x16x32_f16 v[56:59], v[156:159], v[164:167], v[56:59]
	v_mfma_f32_16x16x32_f16 v[44:47], v[148:151], v[192:195], v[44:47]
	v_mfma_f32_16x16x32_f16 v[40:43], v[156:159], v[192:195], v[40:43]
	v_mfma_f32_16x16x32_f16 v[28:31], v[148:151], v[206:209], v[28:31]
	v_mfma_f32_16x16x32_f16 v[24:27], v[156:159], v[206:209], v[24:27]
	v_mfma_f32_16x16x32_f16 v[12:15], v[148:151], v[214:217], v[12:15]
	v_mfma_f32_16x16x32_f16 v[8:11], v[156:159], v[214:217], v[8:11]
	s_setprio 0
	s_barrier
	s_add_i32 s57, 0, 0x18000
	s_add_i32 s58, 0, 0x1c000
	v_add_u32_e32 v124, s57, v197
	v_add_u32_e32 v156, s58, v197
	ds_read_b128 v[112:115], v124
	ds_read_b128 v[116:119], v124 offset:1024
	ds_read_b128 v[120:123], v124 offset:2048
	ds_read_b128 v[124:127], v124 offset:3072
	ds_read_b128 v[144:147], v156
	ds_read_b128 v[148:151], v156 offset:1024
	ds_read_b128 v[152:155], v156 offset:2048
	ds_read_b128 v[156:159], v156 offset:3072
	s_add_u32 s26, s26, 0x40000
	s_addc_u32 s27, s27, 0
	s_mov_b32 m0, s42
	v_lshl_add_u64 v[226:227], s[26:27], 0, v[172:173]
	ds_read_b128 v[160:163], v200 offset:32768
	ds_read_b128 v[164:167], v200 offset:33792
	ds_read_b128 v[168:171], v200 offset:34816
	ds_read_b128 v[192:195], v200 offset:35840
	ds_read_b128 v[202:205], v200 offset:36864
	ds_read_b128 v[206:209], v200 offset:37888
	ds_read_b128 v[210:213], v200 offset:38912
	ds_read_b128 v[214:217], v200 offset:39936
	global_load_lds_dwordx4 v[226:227], off
	v_lshl_add_u64 v[226:227], s[26:27], 0, v[176:177]
	s_mov_b32 m0, s43
	s_nop 0
	global_load_lds_dwordx4 v[226:227], off
	s_waitcnt vmcnt(8)
	s_waitcnt lgkmcnt(0)
	s_barrier
	s_setprio 1
	s_waitcnt lgkmcnt(0)
	v_mfma_f32_16x16x32_f16 v[132:135], v[112:115], v[160:163], v[132:135]
	v_mfma_f32_16x16x32_f16 v[128:131], v[120:123], v[160:163], v[128:131]
	v_mfma_f32_16x16x32_f16 v[100:103], v[112:115], v[168:171], v[100:103]
	v_mfma_f32_16x16x32_f16 v[96:99], v[120:123], v[168:171], v[96:99]
	v_mfma_f32_16x16x32_f16 v[84:87], v[112:115], v[202:205], v[84:87]
	v_mfma_f32_16x16x32_f16 v[80:83], v[120:123], v[202:205], v[80:83]
	v_mfma_f32_16x16x32_f16 v[68:71], v[112:115], v[210:213], v[68:71]
	v_mfma_f32_16x16x32_f16 v[64:67], v[120:123], v[210:213], v[64:67]
	v_mfma_f32_16x16x32_f16 v[132:135], v[116:119], v[164:167], v[132:135]
	v_mfma_f32_16x16x32_f16 v[128:131], v[124:127], v[164:167], v[128:131]
	v_mfma_f32_16x16x32_f16 v[100:103], v[116:119], v[192:195], v[100:103]
	v_mfma_f32_16x16x32_f16 v[96:99], v[124:127], v[192:195], v[96:99]
	v_mfma_f32_16x16x32_f16 v[84:87], v[116:119], v[206:209], v[84:87]
	v_mfma_f32_16x16x32_f16 v[80:83], v[124:127], v[206:209], v[80:83]
	v_mfma_f32_16x16x32_f16 v[68:71], v[116:119], v[214:217], v[68:71]
	v_mfma_f32_16x16x32_f16 v[64:67], v[124:127], v[214:217], v[64:67]
	s_setprio 0
	s_setprio 1
	v_mfma_f32_16x16x32_f16 v[140:143], v[144:147], v[160:163], v[140:143]
	v_mfma_f32_16x16x32_f16 v[136:139], v[152:155], v[160:163], v[136:139]
	v_mfma_f32_16x16x32_f16 v[108:111], v[144:147], v[168:171], v[108:111]
	v_mfma_f32_16x16x32_f16 v[104:107], v[152:155], v[168:171], v[104:107]
	v_mfma_f32_16x16x32_f16 v[92:95], v[144:147], v[202:205], v[92:95]
	v_mfma_f32_16x16x32_f16 v[88:91], v[152:155], v[202:205], v[88:91]
	v_mfma_f32_16x16x32_f16 v[76:79], v[144:147], v[210:213], v[76:79]
	v_mfma_f32_16x16x32_f16 v[72:75], v[152:155], v[210:213], v[72:75]
	v_mfma_f32_16x16x32_f16 v[140:143], v[148:151], v[164:167], v[140:143]
	v_mfma_f32_16x16x32_f16 v[136:139], v[156:159], v[164:167], v[136:139]
	v_mfma_f32_16x16x32_f16 v[108:111], v[148:151], v[192:195], v[108:111]
	v_mfma_f32_16x16x32_f16 v[104:107], v[156:159], v[192:195], v[104:107]
	v_mfma_f32_16x16x32_f16 v[92:95], v[148:151], v[206:209], v[92:95]
	v_mfma_f32_16x16x32_f16 v[88:91], v[156:159], v[206:209], v[88:91]
	v_mfma_f32_16x16x32_f16 v[76:79], v[148:151], v[214:217], v[76:79]
	v_mfma_f32_16x16x32_f16 v[72:75], v[156:159], v[214:217], v[72:75]
	s_setprio 0
	s_barrier
; #define PG8_STAGE(bufoff, gbase, voff) do { _Pragma("unroll") for (int _i = 0; _i < 2; ++_i) \
;         __builtin_amdgcn_global_load_lds((const unsigned*)((const char*)(gbase) + (voff)[_i]), (PG8_LAS unsigned*)(lds + (bufoff) + ldsw + _i * 8192), 16, 0, 0); } while (0)
; #define PG8_LDA(dst, b, h) do { _Pragma("unroll") for (int m = 0; m < 4; ++m) _Pragma("unroll") for (int k = 0; k < 2; ++k) dst[m][k] = *(const PG8_LAS bf16x8*)(lds + PG8_SA(b, h) + aoff + m * 2048 + k * 1024); } while (0)
; #define PG8_WAIT_V(n) asm volatile("s_waitcnt vmcnt(" #n ")" ::: "memory")
; #define PG8_WAIT_L(n) asm volatile("s_waitcnt lgkmcnt(" #n ")" ::: "memory")
; #define PG8_BAR __builtin_amdgcn_s_barrier()
; #define PG8_SCHED __builtin_amdgcn_sched_barrier(0)
;     ...
;         for (int t = 0; t < nt; t += 2) {
;     ...
;             PG8_LDA(At, 1, 1); PG8_STAGE(PG8_SB(1, 0), b3, voffB); PG8_STAGE(PG8_SB(1, 1), b3 + hstepB, voffB); PG8_STAGE(PG8_SA(1, 0), a3, voffA);
;             PG8_WAIT_V(8); PG8_WAIT_L(0); PG8_BAR; PG8_MMA(1, 0, At, B0); PG8_MMA(1, 1, At, B1); PG8_BAR; PG8_SCHED;
;         }
	s_add_i32 s26, s57, s28
	v_lshl_add_u64 v[218:219], v[218:219], 0, s[10:11]
	s_mov_b32 m0, s26
	ds_read_b128 v[160:163], v200 offset:49152
	ds_read_b128 v[164:167], v200 offset:50176
	ds_read_b128 v[168:171], v200 offset:51200
	ds_read_b128 v[192:195], v200 offset:52224
	ds_read_b128 v[202:205], v200 offset:53248
	ds_read_b128 v[206:209], v200 offset:54272
	ds_read_b128 v[210:213], v200 offset:55296
	ds_read_b128 v[214:217], v200 offset:56320
	global_load_lds_dwordx4 v[218:219], off
	s_add_i32 m0, s26, 0x2000
	s_add_u32 s22, s22, 0x10080
	v_lshl_add_u64 v[218:219], v[220:221], 0, s[10:11]
	s_addc_u32 s23, s23, 0
	s_add_i32 s26, s58, s28
	global_load_lds_dwordx4 v[218:219], off
	v_lshl_add_u64 v[218:219], s[22:23], 0, v[174:175]
	s_mov_b32 m0, s26
	s_nop 0
	global_load_lds_dwordx4 v[218:219], off
	v_lshl_add_u64 v[218:219], s[22:23], 0, v[178:179]
	s_add_i32 m0, s26, 0x2000
	s_nop 0
	global_load_lds_dwordx4 v[218:219], off
	v_lshl_add_u64 v[218:219], v[222:223], 0, s[10:11]
	s_mov_b32 m0, s48
	s_nop 0
	global_load_lds_dwordx4 v[218:219], off
	v_lshl_add_u64 v[218:219], v[224:225], 0, s[10:11]
	s_mov_b32 m0, s49
	s_nop 0
	global_load_lds_dwordx4 v[218:219], off
	s_waitcnt vmcnt(8)
	s_waitcnt lgkmcnt(0)
	s_barrier
	s_setprio 1
	s_waitcnt lgkmcnt(0)
	v_mfma_f32_16x16x32_f16 v[52:55], v[112:115], v[160:163], v[52:55]
	v_mfma_f32_16x16x32_f16 v[48:51], v[120:123], v[160:163], v[48:51]
	v_mfma_f32_16x16x32_f16 v[36:39], v[112:115], v[168:171], v[36:39]
	v_mfma_f32_16x16x32_f16 v[32:35], v[120:123], v[168:171], v[32:35]
	v_mfma_f32_16x16x32_f16 v[20:23], v[112:115], v[202:205], v[20:23]
	v_mfma_f32_16x16x32_f16 v[16:19], v[120:123], v[202:205], v[16:19]
	v_mfma_f32_16x16x32_f16 v[4:7], v[112:115], v[210:213], v[4:7]
	v_mfma_f32_16x16x32_f16 v[0:3], v[120:123], v[210:213], v[0:3]
	v_mfma_f32_16x16x32_f16 v[52:55], v[116:119], v[164:167], v[52:55]
	v_mfma_f32_16x16x32_f16 v[48:51], v[124:127], v[164:167], v[48:51]
	v_mfma_f32_16x16x32_f16 v[36:39], v[116:119], v[192:195], v[36:39]
	v_mfma_f32_16x16x32_f16 v[32:35], v[124:127], v[192:195], v[32:35]
	v_mfma_f32_16x16x32_f16 v[20:23], v[116:119], v[206:209], v[20:23]
	v_mfma_f32_16x16x32_f16 v[16:19], v[124:127], v[206:209], v[16:19]
	v_mfma_f32_16x16x32_f16 v[4:7], v[116:119], v[214:217], v[4:7]
	v_mfma_f32_16x16x32_f16 v[0:3], v[124:127], v[214:217], v[0:3]
	s_setprio 0
	s_setprio 1
	v_mfma_f32_16x16x32_f16 v[60:63], v[144:147], v[160:163], v[60:63]
	v_mfma_f32_16x16x32_f16 v[56:59], v[152:155], v[160:163], v[56:59]
	v_mfma_f32_16x16x32_f16 v[44:47], v[144:147], v[168:171], v[44:47]
	v_mfma_f32_16x16x32_f16 v[40:43], v[152:155], v[168:171], v[40:43]
	v_mfma_f32_16x16x32_f16 v[28:31], v[144:147], v[202:205], v[28:31]
	v_mfma_f32_16x16x32_f16 v[24:27], v[152:155], v[202:205], v[24:27]
	v_mfma_f32_16x16x32_f16 v[12:15], v[144:147], v[210:213], v[12:15]
	v_mfma_f32_16x16x32_f16 v[8:11], v[152:155], v[210:213], v[8:11]
	v_mfma_f32_16x16x32_f16 v[60:63], v[148:151], v[164:167], v[60:63]
	v_mfma_f32_16x16x32_f16 v[56:59], v[156:159], v[164:167], v[56:59]
	v_mfma_f32_16x16x32_f16 v[44:47], v[148:151], v[192:195], v[44:47]
	v_mfma_f32_16x16x32_f16 v[40:43], v[156:159], v[192:195], v[40:43]
	v_mfma_f32_16x16x32_f16 v[28:31], v[148:151], v[206:209], v[28:31]
	v_mfma_f32_16x16x32_f16 v[24:27], v[156:159], v[206:209], v[24:27]
	v_mfma_f32_16x16x32_f16 v[12:15], v[148:151], v[214:217], v[12:15]
	v_mfma_f32_16x16x32_f16 v[8:11], v[156:159], v[214:217], v[8:11]
	s_setprio 0
	s_barrier
	s_cmp_eq_u32 s101, 0
	s_cbranch_scc1 .Lpkb_t
	s_sub_u32 s101, s101, 1
.Lpkb_t:
	s_add_i32 s56, s56, 2
	s_add_u32 s24, s24, 0x100
	s_addc_u32 s25, s25, 0
	s_add_u32 s39, s39, 0x100
	s_addc_u32 s55, s55, 0
	s_cmp_gt_u32 s56, 13
	s_cbranch_scc0 .LBB0_532
	s_and_b64 vcc, exec, s[14:15]
	s_cbranch_vccz .LBB0_535
	s_barrier

; __device__ __forceinline__ float sum_x16(float v) { float a, b; swap16(v, a, b); return a + b; }
; __device__ __forceinline__ float sum_x32(float v) { float a, b; swap32(v, a, b); return a + b; }
; __device__ __forceinline__ void st16_wt(void* p, u32x4 v) { if (WT_STORES) asm volatile("global_store_dwordx4 %0, %1, off sc1\n\ts_nop 1" :: "v"(p), "v"(v) : "memory"); else *(u32x4*)p = v; }
; __device__ __forceinline__ unsigned cvt_pk_bf16(float lo, float hi) { unsigned r; asm volatile("v_cvt_pk_bf16_f32 %0, %1, %2" : "=v"(r) : "v"(lo), "v"(hi)); return r; }
;     __device__ __forceinline__ void operator()(const f32x4 (&acc)[2][2][4][2], const Unit& u, int wr, int wc, int fr, int fq, const bool reuse, PG8_LAS float* rscr, PG8_LAS const float* gains) const {
;     ...
;         for (int ai = 0; ai < 2; ++ai)
; #pragma unroll
;             for (int m = 0; m < 4; ++m) {
;                 const int r = u.pm * BM + ai * HALF + wr * 64 + m * 16 + fr;
;                 const float rsv = (MODE == 0) ? 1.0f : rsvv[ai][m];
;                 f32x4 v[2][2];
; #pragma unroll
;                 for (int bj = 0; bj < 2; ++bj)
; #pragma unroll
;                     for (int n = 0; n < 2; ++n) v[bj][n] = acc[ai][bj][m][n] * rsv;
;                 if (type < 2) {
;                     float ss = 0.f;
; #pragma unroll
;                     for (int bj = 0; bj < 2; ++bj)
; #pragma unroll
;                         for (int n = 0; n < 2; ++n) { const f32x4 x = v[bj][n]; ss += (x[0] * x[0] + x[1] * x[1]) + (x[2] * x[2] + x[3] * x[3]); }
;                     ss = sum_x16(ss); ss = sum_x32(ss);
;                     const float inv = __builtin_amdgcn_rsqf(ss * (1.0f / 64.0f) + RMS_EPS);
; #pragma unroll
;                     for (int bj = 0; bj < 2; ++bj)
; #pragma unroll
;                         for (int n = 0; n < 2; ++n) v[bj][n] = v[bj][n] * gv[bj][n] * inv;
;                 }
;                 bf16_t* p = p0 + (size_t)(8 * ai + m) * step16;
; #pragma unroll
;                 for (int bj = 0; bj < 2; ++bj) { u32x4 w; w.x = cvt_pk_bf16(v[bj][0][0], v[bj][0][1]); w.y = cvt_pk_bf16(v[bj][0][2], v[bj][0][3]); w.z = cvt_pk_bf16(v[bj][1][0], v[bj][1][1]); w.w = cvt_pk_bf16(v[bj][1][2], v[bj][1][3]);
;                     st16_wt(p + 32 * bj, w); }
.LBB0_573:
	v_lshl_add_u64 v[32:33], v[48:49], 0, s[12:13]
	v_mov_b32_e32 v254, v32
	v_mov_b32_e32 v255, v33
	s_mov_b32 s100, s12
	v_cvt_pk_bf16_f32 v46, v52, v53
	v_cvt_pk_bf16_f32 v47, v38, v39
	v_cvt_pk_bf16_f32 v48, v54, v55
	v_cvt_pk_bf16_f32 v49, v50, v51
	v_mov_b32_e32 v228, v46
	v_mov_b32_e32 v229, v47
	v_mov_b32_e32 v230, v48
	v_mov_b32_e32 v231, v49
	v_cvt_pk_bf16_f32 v38, v44, v45
	v_cvt_pk_bf16_f32 v39, v34, v35
	v_cvt_pk_bf16_f32 v40, v40, v41
	v_cvt_pk_bf16_f32 v41, v36, v37
	v_mov_b32_e32 v232, v38
	v_mov_b32_e32 v233, v39
	v_mov_b32_e32 v234, v40
	v_mov_b32_e32 v235, v41
	v_pk_mul_f32 v[22:23], v[22:23], v[148:149] op_sel_hi:[1,0]
	v_pk_mul_f32 v[36:37], v[20:21], v[148:149] op_sel_hi:[1,0]
	v_pk_mul_f32 v[34:35], v[18:19], v[148:149] op_sel_hi:[1,0]
	v_pk_mul_f32 v[38:39], v[16:17], v[148:149] op_sel_hi:[1,0]
	v_pk_mul_f32 v[18:19], v[30:31], v[148:149] op_sel_hi:[1,0]
	v_pk_mul_f32 v[28:29], v[28:29], v[148:149] op_sel_hi:[1,0]
	v_pk_mul_f32 v[20:21], v[26:27], v[148:149] op_sel_hi:[1,0]
	s_and_b64 vcc, exec, s[38:39]
	v_pk_mul_f32 v[24:25], v[24:25], v[148:149] op_sel_hi:[1,0]
	s_cbranch_vccnz .LBB0_575
	v_mul_f32_e32 v16, v37, v37
	v_mul_f32_e32 v17, v23, v23
	v_fmac_f32_e32 v16, v36, v36
	v_fmac_f32_e32 v17, v22, v22
	v_add_f32_e32 v16, v16, v17
	v_mul_f32_e32 v17, v39, v39
	v_mul_f32_e32 v26, v35, v35
	v_fmac_f32_e32 v17, v38, v38
	v_fmac_f32_e32 v26, v34, v34
	v_add_f32_e32 v17, v17, v26
	v_add_f32_e32 v16, v16, v17
	v_mul_f32_e32 v17, v29, v29
	v_mul_f32_e32 v26, v19, v19
	v_fmac_f32_e32 v17, v28, v28
	v_fmac_f32_e32 v26, v18, v18
	v_add_f32_e32 v17, v17, v26
	v_add_f32_e32 v16, v17, v16
	v_mul_f32_e32 v17, v25, v25
	v_mul_f32_e32 v26, v21, v21
	v_fmac_f32_e32 v17, v24, v24
	v_fmac_f32_e32 v26, v20, v20
	v_add_f32_e32 v17, v17, v26
	v_add_f32_e32 v16, v17, v16
	v_mov_b32_e32 v17, v16
	s_nop 1
	v_permlane16_swap_b32_e32 v16, v17
	v_add_f32_e32 v16, v16, v17
	v_mov_b32_e32 v17, v16
	s_nop 1
	v_permlane32_swap_b32_e32 v16, v17
	v_add_f32_e32 v16, v16, v17
	v_fmamk_f32 v16, v16, 0x3c800000, v201
	v_rsq_f32_e32 v16, v16
	s_waitcnt lgkmcnt(0)
	v_pk_mul_f32 v[26:27], v[124:125], v[36:37]
	v_pk_mul_f32 v[22:23], v[126:127], v[22:23]
	v_pk_mul_f32 v[30:31], v[120:121], v[38:39]
	v_pk_mul_f32 v[36:37], v[26:27], v[16:17] op_sel_hi:[1,0]
	v_pk_mul_f32 v[26:27], v[122:123], v[34:35]
	v_pk_mul_f32 v[18:19], v[118:119], v[18:19]
	v_pk_mul_f32 v[34:35], v[26:27], v[16:17] op_sel_hi:[1,0]
	v_pk_mul_f32 v[26:27], v[116:117], v[28:29]
	v_pk_mul_f32 v[20:21], v[114:115], v[20:21]
	v_pk_mul_f32 v[24:25], v[112:113], v[24:25]
	v_pk_mul_f32 v[22:23], v[22:23], v[16:17] op_sel_hi:[1,0]
	v_pk_mul_f32 v[38:39], v[30:31], v[16:17] op_sel_hi:[1,0]
	v_pk_mul_f32 v[18:19], v[18:19], v[16:17] op_sel_hi:[1,0]
	v_pk_mul_f32 v[28:29], v[26:27], v[16:17] op_sel_hi:[1,0]
	v_pk_mul_f32 v[20:21], v[20:21], v[16:17] op_sel_hi:[1,0]
	v_pk_mul_f32 v[24:25], v[24:25], v[16:17] op_sel_hi:[1,0]
; __device__ __forceinline__ void st16_wt(void* p, u32x4 v) { if (WT_STORES) asm volatile("global_store_dwordx4 %0, %1, off sc1\n\ts_nop 1" :: "v"(p), "v"(v) : "memory"); else *(u32x4*)p = v; }
; __device__ __forceinline__ unsigned cvt_pk_bf16(float lo, float hi) { unsigned r; asm volatile("v_cvt_pk_bf16_f32 %0, %1, %2" : "=v"(r) : "v"(lo), "v"(hi)); return r; }
; #define PG8_ZERO4(x) do { unsigned long long z0_, z1_; asm volatile("v_mov_b64 %0, 0\n\tv_mov_b64 %1, 0" : "=v"(z0_), "=v"(z1_)); typedef unsigned long long u64x2_ __attribute__((ext_vector_type(2))); (x) = __builtin_bit_cast(f32x4, (u64x2_){z0_, z1_}); } while (0)
; #define PG8_BAR __builtin_amdgcn_s_barrier()
;     __device__ __forceinline__ void operator()(const f32x4 (&acc)[2][2][4][2], const Unit& u, int wr, int wc, int fr, int fq, const bool reuse, PG8_LAS float* rscr, PG8_LAS const float* gains) const {
;     ...
;                 bf16_t* p = p0 + (size_t)(8 * ai + m) * step16;
; #pragma unroll
;                 for (int bj = 0; bj < 2; ++bj) { u32x4 w; w.x = cvt_pk_bf16(v[bj][0][0], v[bj][0][1]); w.y = cvt_pk_bf16(v[bj][0][2], v[bj][0][3]); w.z = cvt_pk_bf16(v[bj][1][0], v[bj][1][1]); w.w = cvt_pk_bf16(v[bj][1][2], v[bj][1][3]);
;                     st16_wt(p + 32 * bj, w); }
;     ...
;         if (!has_next) break;
; #pragma unroll
;         for (int a = 0; a < 2; ++a)
; #pragma unroll
;             for (int b = 0; b < 2; ++b)
; #pragma unroll
;                 for (int m = 0; m < 4; ++m)
; #pragma unroll
;                     for (int n = 0; n < 2; ++n) PG8_ZERO4(acc[a][b][m][n]);
;         cur = nxt; cA = nA; cB = nB; ++ui;
;         if constexpr (ALIGN_EPI) { if (wr == 1) PG8_BAR; }
;     }
.LBB0_575:
	v_lshl_add_u64 v[16:17], v[32:33], 0, s[12:13]
	v_cvt_pk_bf16_f32 v30, v36, v37
	v_cvt_pk_bf16_f32 v31, v22, v23
	v_cvt_pk_bf16_f32 v32, v38, v39
	v_cvt_pk_bf16_f32 v33, v34, v35
	v_mov_b32_e32 v236, v30
	v_mov_b32_e32 v237, v31
	v_mov_b32_e32 v238, v32
	v_mov_b32_e32 v239, v33
	v_cvt_pk_bf16_f32 v22, v28, v29
	v_cvt_pk_bf16_f32 v23, v18, v19
	v_cvt_pk_bf16_f32 v24, v24, v25
	v_cvt_pk_bf16_f32 v25, v20, v21
	v_pk_mul_f32 v[6:7], v[6:7], v[144:145] op_sel_hi:[1,0]
	v_pk_mul_f32 v[18:19], v[4:5], v[144:145] op_sel_hi:[1,0]
	v_pk_mul_f32 v[4:5], v[2:3], v[144:145] op_sel_hi:[1,0]
	v_pk_mul_f32 v[20:21], v[0:1], v[144:145] op_sel_hi:[1,0]
	v_pk_mul_f32 v[0:1], v[14:15], v[144:145] op_sel_hi:[1,0]
	v_pk_mul_f32 v[12:13], v[12:13], v[144:145] op_sel_hi:[1,0]
	v_pk_mul_f32 v[2:3], v[10:11], v[144:145] op_sel_hi:[1,0]
	s_and_b64 vcc, exec, s[38:39]
	v_pk_mul_f32 v[8:9], v[8:9], v[144:145] op_sel_hi:[1,0]
	v_mov_b32_e32 v240, v22
	v_mov_b32_e32 v241, v23
	v_mov_b32_e32 v242, v24
	v_mov_b32_e32 v243, v25
	s_cbranch_vccnz .LBB0_577
	v_mul_f32_e32 v10, v19, v19
	v_mul_f32_e32 v11, v7, v7
	v_fmac_f32_e32 v10, v18, v18
	v_fmac_f32_e32 v11, v6, v6
	v_add_f32_e32 v10, v10, v11
	v_mul_f32_e32 v11, v21, v21
	v_mul_f32_e32 v14, v5, v5
	v_fmac_f32_e32 v11, v20, v20
	v_fmac_f32_e32 v14, v4, v4
	v_add_f32_e32 v11, v11, v14
	v_add_f32_e32 v10, v10, v11
	v_mul_f32_e32 v11, v13, v13
	v_mul_f32_e32 v14, v1, v1
	v_fmac_f32_e32 v11, v12, v12
	v_fmac_f32_e32 v14, v0, v0
	v_add_f32_e32 v11, v11, v14
	v_add_f32_e32 v10, v11, v10
	v_mul_f32_e32 v11, v9, v9
	v_mul_f32_e32 v14, v3, v3
	v_fmac_f32_e32 v11, v8, v8
	v_fmac_f32_e32 v14, v2, v2
	v_add_f32_e32 v11, v11, v14
	v_add_f32_e32 v10, v11, v10
	v_mov_b32_e32 v11, v10
	s_nop 1
	v_permlane16_swap_b32_e32 v10, v11
	v_add_f32_e32 v10, v10, v11
	v_mov_b32_e32 v11, v10
	s_nop 1
	v_permlane32_swap_b32_e32 v10, v11
	v_add_f32_e32 v10, v10, v11
	v_fmamk_f32 v10, v10, 0x3c800000, v201
	v_rsq_f32_e32 v10, v10
	s_waitcnt lgkmcnt(0)
	v_pk_mul_f32 v[14:15], v[124:125], v[18:19]
	v_pk_mul_f32 v[6:7], v[126:127], v[6:7]
	v_pk_mul_f32 v[4:5], v[122:123], v[4:5]
	v_pk_mul_f32 v[18:19], v[14:15], v[10:11] op_sel_hi:[1,0]
	v_pk_mul_f32 v[14:15], v[120:121], v[20:21]
	v_pk_mul_f32 v[0:1], v[118:119], v[0:1]
	v_pk_mul_f32 v[12:13], v[116:117], v[12:13]
	v_pk_mul_f32 v[2:3], v[114:115], v[2:3]
	v_pk_mul_f32 v[8:9], v[112:113], v[8:9]
	v_pk_mul_f32 v[6:7], v[6:7], v[10:11] op_sel_hi:[1,0]
	v_pk_mul_f32 v[4:5], v[4:5], v[10:11] op_sel_hi:[1,0]
	v_pk_mul_f32 v[20:21], v[14:15], v[10:11] op_sel_hi:[1,0]
	v_pk_mul_f32 v[0:1], v[0:1], v[10:11] op_sel_hi:[1,0]
	v_pk_mul_f32 v[12:13], v[12:13], v[10:11] op_sel_hi:[1,0]
	v_pk_mul_f32 v[2:3], v[2:3], v[10:11] op_sel_hi:[1,0]
	v_pk_mul_f32 v[8:9], v[8:9], v[10:11] op_sel_hi:[1,0]
.LBB0_577:
	v_lshl_add_u64 v[10:11], v[16:17], 0, s[12:13]
	v_cvt_pk_bf16_f32 v14, v18, v19
	v_cvt_pk_bf16_f32 v15, v6, v7
	v_cvt_pk_bf16_f32 v16, v20, v21
	v_cvt_pk_bf16_f32 v17, v4, v5
	v_mov_b32_e32 v244, v14
	v_mov_b32_e32 v245, v15
	v_mov_b32_e32 v246, v16
	v_mov_b32_e32 v247, v17
	v_cvt_pk_bf16_f32 v4, v12, v13
	v_cvt_pk_bf16_f32 v5, v0, v1
	v_cvt_pk_bf16_f32 v6, v8, v9
	v_cvt_pk_bf16_f32 v7, v2, v3
	s_andn2_b64 vcc, exec, s[36:37]
	s_mov_b64 s[22:23], -1
	v_mov_b32_e32 v248, v4
	v_mov_b32_e32 v249, v5
	v_mov_b32_e32 v250, v6
	v_mov_b32_e32 v251, v7
	s_mov_b32 s101, 6
	s_cbranch_vccnz .LBB0_524
	s_andn2_b64 vcc, exec, s[8:9]
	v_mov_b64 v[132:133], 0
	v_mov_b64 v[134:135], 0
	v_mov_b64 v[128:129], 0
	v_mov_b64 v[130:131], 0
	v_mov_b64 v[100:101], 0
	v_mov_b64 v[102:103], 0
	v_mov_b64 v[96:97], 0
	v_mov_b64 v[98:99], 0
	v_mov_b64 v[84:85], 0
	v_mov_b64 v[86:87], 0
	v_mov_b64 v[80:81], 0
	v_mov_b64 v[82:83], 0
	v_mov_b64 v[68:69], 0
	v_mov_b64 v[70:71], 0
	v_mov_b64 v[64:65], 0
	v_mov_b64 v[66:67], 0
	v_mov_b64 v[140:141], 0
	v_mov_b64 v[142:143], 0
	v_mov_b64 v[136:137], 0
	v_mov_b64 v[138:139], 0
	v_mov_b64 v[108:109], 0
	v_mov_b64 v[110:111], 0
	v_mov_b64 v[104:105], 0
	v_mov_b64 v[106:107], 0
	v_mov_b64 v[92:93], 0
	v_mov_b64 v[94:95], 0
	v_mov_b64 v[88:89], 0
	v_mov_b64 v[90:91], 0
	v_mov_b64 v[76:77], 0
	v_mov_b64 v[78:79], 0
	v_mov_b64 v[72:73], 0
	v_mov_b64 v[74:75], 0
	v_mov_b64 v[52:53], 0
	v_mov_b64 v[54:55], 0
	v_mov_b64 v[48:49], 0
	v_mov_b64 v[50:51], 0
	v_mov_b64 v[36:37], 0
	v_mov_b64 v[38:39], 0
	v_mov_b64 v[32:33], 0
	v_mov_b64 v[34:35], 0
	v_mov_b64 v[20:21], 0
	v_mov_b64 v[22:23], 0
	v_mov_b64 v[16:17], 0
	v_mov_b64 v[18:19], 0
	v_mov_b64 v[4:5], 0
	v_mov_b64 v[6:7], 0
	v_mov_b64 v[0:1], 0
	v_mov_b64 v[2:3], 0
	v_mov_b64 v[60:61], 0
	v_mov_b64 v[62:63], 0
	v_mov_b64 v[56:57], 0
	v_mov_b64 v[58:59], 0
	v_mov_b64 v[44:45], 0
	v_mov_b64 v[46:47], 0
	v_mov_b64 v[40:41], 0
	v_mov_b64 v[42:43], 0
	v_mov_b64 v[28:29], 0
	v_mov_b64 v[30:31], 0
	v_mov_b64 v[24:25], 0
	v_mov_b64 v[26:27], 0
	v_mov_b64 v[12:13], 0
	v_mov_b64 v[14:15], 0
	v_mov_b64 v[8:9], 0
	v_mov_b64 v[10:11], 0
	s_cbranch_vccnz .LBB0_523
	s_barrier
	s_branch .LBB0_523
.LBB0_580:
	s_cmp_eq_u32 s101, 0
	s_cbranch_scc1 .Lpkb_fd
	global_store_dwordx4 v[254:255], v[228:231], off
	global_store_dwordx4 v[254:255], v[232:235], off offset:64
	v_add_co_u32_e32 v254, vcc, s100, v254
	s_nop 1
	v_addc_co_u32_e32 v255, vcc, 0, v255, vcc
	global_store_dwordx4 v[254:255], v[236:239], off
	global_store_dwordx4 v[254:255], v[240:243], off offset:64
	v_add_co_u32_e32 v254, vcc, s100, v254
	s_nop 1
	v_addc_co_u32_e32 v255, vcc, 0, v255, vcc
	global_store_dwordx4 v[254:255], v[244:247], off
	global_store_dwordx4 v[254:255], v[248:251], off offset:64
	s_mov_b32 s101, 0

; #define LAS __attribute__((address_space(3)))
; __device__ __forceinline__ void tbl_b(int u, int tblbuf, const float* rpb, float cshift, LAS char* lds, int tid) {
;     const int h = (u >> 3) & 15;
;     for (int idx = tid; idx < 640; idx += NWAVES * 64) {
;         float v = NEG; const int e = idx - 16;
;         if (e >= 0 && e < 480 && (e & 31) < 31) v = LOG2E * rpb[(h * 15 + (e >> 5)) * 31 + (e & 31)] - cshift;
;         ((LAS float*)(lds + TBL_OFF + tblbuf * TBL_BYTES))[idx] = v;
;     }
; }
.LBB0_632:
	s_or_b64 exec, exec, s[10:11]
	v_add_u32_e32 v2, 0x200, v2
	v_cmp_lt_i32_e32 vcc, s15, v2
	ds_write_b32 v3, v5
	ds_write_b32 v3, v5 offset:4096
	s_or_b64 s[6:7], vcc, s[6:7]
	v_add_u32_e32 v3, 0x800, v3
	s_andn2_b64 exec, exec, s[6:7]
	s_cbranch_execz .LBB0_635

; __device__ __forceinline__ void unit_b(UnitB& U, int u, const bf16* qkv) {
;     U.R = u & 7; U.h = (u >> 3) & 15; U.b = u >> 7;
;     const int kr0 = min(max(8 * U.R - 4, 0), 56), krl = min(max(8 * U.R + 7 - 4, 0), 56) + 7;
;     U.nrows = krl - kr0 + 1;
;     const bf16* Qb = qkv + ((size_t)(U.b * 16 + U.h) * 4096) * 64;
;     U.Kr = uniform_ptr(Qb + SECB + (size_t)kr0 * 4096); U.Vr = uniform_ptr(Qb + 2 * SECB + (size_t)kr0 * 4096);
; }
; __device__ __forceinline__ void attn_b_phase(Frame& F, const float cshift, const bf16* qkv, const bf16* gate, bf16* y, const float* rpb, const float* qg, const float* kg) {
;     ...
;     tbl_b(u0, 0, rpb, cshift, lds, tid);
;     UnitB cur, nxt; unit_b(cur, u0, qkv); nxt = cur;
;     if (nu > 1) unit_b(nxt, u0 + 1, qkv);
.LBB0_635:
	s_or_b64 exec, exec, s[4:5]
	s_mov_b32 s101, 1
	s_and_b32 s59, s41, 7
	s_lshl_b32 s4, s59, 3
	s_max_u32 s5, s4, 4
	v_sub_u32_e64 v2, s4, 4 clamp
	s_or_b32 s4, s4, 3
	s_min_u32 s4, s4, 56
	s_ashr_i32 s20, s41, 7
	s_sub_i32 s4, s4, s5
	s_add_i32 s21, s4, 12
	s_lshl_b32 s4, s20, 4
	s_or_b32 s4, s4, s58
	s_ashr_i32 s5, s4, 31
	s_lshl_b64 s[4:5], s[4:5], 19
	s_add_u32 s16, s33, s4
	s_addc_u32 s17, s40, s5
	v_lshlrev_b32_e32 v146, 13, v2
	v_mov_b32_e32 v147, 0
	v_lshl_add_u64 v[2:3], s[16:17], 0, v[146:147]
	s_mov_b64 s[4:5], 0x4000000
	s_mov_b64 s[6:7], 0x8000000
	v_lshl_add_u64 v[4:5], v[2:3], 0, s[4:5]
	v_lshl_add_u64 v[2:3], v[2:3], 0, s[6:7]
	v_readfirstlane_b32 s27, v5
	v_readfirstlane_b32 s26, v4
	v_readfirstlane_b32 s29, v3
	v_readfirstlane_b32 s28, v2
	s_cmp_eq_u32 s42, 1
	s_mov_b32 s43, s59
	s_mov_b32 s48, s21
	s_mov_b64 s[10:11], s[28:29]
	s_mov_b64 s[8:9], s[26:27]
	s_mov_b32 s44, s58
	s_mov_b32 s45, s20
	s_cbranch_scc1 .LBB0_637
	s_add_i32 s8, s41, 1
	s_and_b32 s43, s8, 7
	s_bfe_u32 s44, s8, 0x40003
	s_ashr_i32 s45, s8, 7
	s_lshl_b32 s8, s43, 3
	s_max_u32 s9, s8, 4
	v_sub_u32_e64 v2, s8, 4 clamp
	s_or_b32 s8, s8, 3
	s_min_u32 s8, s8, 56
	s_sub_i32 s8, s8, s9
	s_add_i32 s48, s8, 12
	s_lshl_b32 s8, s45, 4
	s_or_b32 s8, s8, s44
	s_ashr_i32 s9, s8, 31
	s_lshl_b64 s[8:9], s[8:9], 19
	s_add_u32 s8, s33, s8
	s_addc_u32 s9, s40, s9
	v_lshlrev_b32_e32 v146, 13, v2
	v_lshl_add_u64 v[2:3], s[8:9], 0, v[146:147]
	v_lshl_add_u64 v[4:5], v[2:3], 0, s[4:5]
	v_lshl_add_u64 v[2:3], v[2:3], 0, s[6:7]
	v_readfirstlane_b32 s9, v5
	v_readfirstlane_b32 s8, v4
	v_readfirstlane_b32 s11, v3
	v_readfirstlane_b32 s10, v2

; __device__ __forceinline__ float sum_x32(float v) { float a, b; swap32(v, a, b); return a + b; }
; #define LAS __attribute__((address_space(3)))
; __device__ __forceinline__ unsigned cvtpk(float lo, float hi) { f32x2_t v = {lo, hi}; bf16x2_t b = __builtin_convertvector(v, bf16x2_t); return __builtin_bit_cast(unsigned, b); }
; __device__ __forceinline__ void acc_block(const bool FIRST, const f32x16& o0, const f32x16& o1, float lsum, LAS char* lds, int tloc, int lane) {
;     const int hi = lane >> 5;
;     LAS char* row = lds + ACC_OFF + rho(tloc) * ACC_PITCH + 8 * hi;
; #pragma unroll
;     for (int dh = 0; dh < 2; ++dh)
; #pragma unroll
;         for (int c4 = 0; c4 < 4; ++c4) {
;             float v0 = dh ? o1[4 * c4] : o0[4 * c4], v1 = dh ? o1[4 * c4 + 1] : o0[4 * c4 + 1], v2 = dh ? o1[4 * c4 + 2] : o0[4 * c4 + 2], v3 = dh ? o1[4 * c4 + 3] : o0[4 * c4 + 3];
;             LAS v2u* a = (LAS v2u*)(row + 64 * dh + 16 * c4);
;             if (!FIRST) { const v2u old = *a; v0 += __builtin_bit_cast(float, old.x << 16); v1 += __builtin_bit_cast(float, old.x & 0xffff0000u); v2 += __builtin_bit_cast(float, old.y << 16); v3 += __builtin_bit_cast(float, old.y & 0xffff0000u); }
;             v2u w; w.x = cvtpk(v0, v1); w.y = cvtpk(v2, v3); *a = w;
;         }
;     float l = sum_x32(lsum);
;     if (hi == 0) { LAS float* la = (LAS float*)(lds + LACC_OFF) + tloc; if (!FIRST) l += *la; *la = l; }
; }
; __device__ __forceinline__ void attn_b_phase(Frame& F, const float cshift, const bf16* qkv, const bf16* gate, bf16* y, const float* rpb, const float* qg, const float* kg) {
;     ...
;         acc_block(true, oA0, oA1, lA, lds, tlocA, lane);
;         acc_block(true, oB0, oB1, lB, lds, tlocB, lane);
;         if (more) tbl_b(u + 1, (ui + 1) & 1, rpb, cshift, lds, tid);
.LBB0_657:
	v_cvt_pk_bf16_f32 v32, v32, v33
	v_cvt_pk_bf16_f32 v33, v34, v35
	v_cvt_pk_bf16_f32 v34, v36, v37
	v_cvt_pk_bf16_f32 v35, v38, v39
	ds_write2_b64 v206, v[32:33], v[34:35] offset0:8 offset1:10
	v_cvt_pk_bf16_f32 v32, v40, v41
	v_cvt_pk_bf16_f32 v33, v42, v43
	v_cvt_pk_bf16_f32 v34, v44, v45
	v_cvt_pk_bf16_f32 v35, v46, v47
	v_cvt_pk_bf16_f32 v48, v48, v49
	v_cvt_pk_bf16_f32 v49, v50, v51
	v_cvt_pk_bf16_f32 v50, v52, v53
	v_cvt_pk_bf16_f32 v51, v54, v55
	ds_write2_b64 v206, v[32:33], v[34:35] offset0:12 offset1:14
	v_mov_b32_e32 v32, v176
	ds_write2_b64 v206, v[48:49], v[50:51] offset1:2
	v_cvt_pk_bf16_f32 v48, v56, v57
	v_cvt_pk_bf16_f32 v49, v58, v59
	v_cvt_pk_bf16_f32 v50, v60, v61
	v_cvt_pk_bf16_f32 v51, v62, v63
	v_permlane32_swap_b32_e32 v176, v32
	ds_write2_b64 v206, v[48:49], v[50:51] offset0:4 offset1:6
	s_and_saveexec_b64 s[24:25], s[36:37]
	v_add_f32_e32 v32, v176, v32
	ds_write_b32 v201, v32
	s_or_b64 exec, exec, s[24:25]
	v_cvt_pk_bf16_f32 v0, v0, v1
	v_cvt_pk_bf16_f32 v1, v2, v3
	v_cvt_pk_bf16_f32 v2, v4, v5
	v_cvt_pk_bf16_f32 v3, v6, v7
	ds_write2_b64 v207, v[0:1], v[2:3] offset0:8 offset1:10
	v_cvt_pk_bf16_f32 v0, v8, v9
	v_cvt_pk_bf16_f32 v1, v10, v11
	v_cvt_pk_bf16_f32 v2, v12, v13
	v_cvt_pk_bf16_f32 v3, v14, v15
	v_cvt_pk_bf16_f32 v16, v16, v17
	v_cvt_pk_bf16_f32 v17, v18, v19
	v_cvt_pk_bf16_f32 v18, v20, v21
	v_cvt_pk_bf16_f32 v19, v22, v23
	ds_write2_b64 v207, v[0:1], v[2:3] offset0:12 offset1:14
	v_mov_b32_e32 v0, v64
	ds_write2_b64 v207, v[16:17], v[18:19] offset1:2
	v_cvt_pk_bf16_f32 v16, v24, v25
	v_cvt_pk_bf16_f32 v17, v26, v27
	v_cvt_pk_bf16_f32 v18, v28, v29
	v_cvt_pk_bf16_f32 v19, v30, v31
	v_permlane32_swap_b32_e32 v64, v0
	ds_write2_b64 v207, v[16:17], v[18:19] offset0:4 offset1:6
	s_and_saveexec_b64 s[24:25], s[36:37]
	v_add_f32_e32 v0, v64, v0
	ds_write_b32 v202, v0
	s_or_b64 exec, exec, s[24:25]
	s_add_i32 s28, s57, s41
	s_nor_b64 s[24:25], s[34:35], s[22:23]
	s_and_saveexec_b64 s[22:23], s[24:25]
	s_cbranch_execz .LBB0_666
	s_add_i32 s2, s28, 1
	s_bfe_u32 s2, s2, 0x40003
	s_bfe_u32 s12, s28, 0x40003
	s_cmp_lg_u32 s2, s12
	s_cbranch_scc1 .Ltb_refill
	s_cmp_eq_u32 s101, 1
	s_cbranch_scc1 .LBB0_666
.Ltb_refill:
	s_mov_b32 s101, 0
	s_and_b32 s2, s53, 0x1000
	v_add_u32_e32 v0, s2, v205
	s_add_i32 s2, s28, 1
	s_bfe_u32 s2, s2, 0x40003
	s_mul_i32 s2, s2, 15
	s_mov_b64 s[24:25], 0
	v_mov_b32_e32 v1, v204
	s_branch .LBB0_664

; __global__ void __launch_bounds__(NWAVES * 64, 2) fwd_kernel(Args args) {
;     extern __shared__ __attribute__((aligned(16))) unsigned char lds[];
	.amdhsa_kernel _Z10fwd_kernel4Args
		.amdhsa_group_segment_fixed_size 0
		.amdhsa_private_segment_fixed_size 0
		.amdhsa_kernarg_size 376
		.amdhsa_user_sgpr_count 2
		.amdhsa_user_sgpr_dispatch_ptr 0
		.amdhsa_user_sgpr_queue_ptr 0
		.amdhsa_user_sgpr_kernarg_segment_ptr 1
		.amdhsa_user_sgpr_dispatch_id 0
		.amdhsa_user_sgpr_kernarg_preload_length 0
		.amdhsa_user_sgpr_kernarg_preload_offset 0
		.amdhsa_user_sgpr_private_segment_size 0
		.amdhsa_uses_dynamic_stack 0
		.amdhsa_enable_private_segment 0
		.amdhsa_system_sgpr_workgroup_id_x 1
		.amdhsa_system_sgpr_workgroup_id_y 0
		.amdhsa_system_sgpr_workgroup_id_z 0
		.amdhsa_system_sgpr_workgroup_info 0
		.amdhsa_system_vgpr_workitem_id 0
		.amdhsa_next_free_vgpr 256
		.amdhsa_next_free_sgpr 102
		.amdhsa_accum_offset 256
		.amdhsa_reserve_vcc 1
		.amdhsa_float_round_mode_32 0
		.amdhsa_float_round_mode_16_64 0
		.amdhsa_float_denorm_mode_32 3
		.amdhsa_float_denorm_mode_16_64 3
		.amdhsa_dx10_clamp 1
		.amdhsa_ieee_mode 1
		.amdhsa_fp16_overflow 0
		.amdhsa_tg_split 0
		.amdhsa_exception_fp_ieee_invalid_op 0
		.amdhsa_exception_fp_denorm_src 0
		.amdhsa_exception_fp_ieee_div_zero 0
		.amdhsa_exception_fp_ieee_overflow 0
		.amdhsa_exception_fp_ieee_underflow 0
		.amdhsa_exception_fp_ieee_inexact 0
		.amdhsa_exception_int_div_zero 0
	.end_amdhsa_kernel

; __global__ void __launch_bounds__(NWAVES * 64, 2) fwd_kernel(Args args) {
;     extern __shared__ __attribute__((aligned(16))) unsigned char lds[];
amdhsa.kernels:
  - .agpr_count:     0
    .args:
      - .offset:         0
        .size:           120
        .value_kind:     by_value
      - .offset:         120
        .size:           4
        .value_kind:     hidden_block_count_x
      - .offset:         124
        .size:           4
        .value_kind:     hidden_block_count_y
      - .offset:         128
        .size:           4
        .value_kind:     hidden_block_count_z
      - .offset:         132
        .size:           2
        .value_kind:     hidden_group_size_x
      - .offset:         134
        .size:           2
        .value_kind:     hidden_group_size_y
      - .offset:         136
        .size:           2
        .value_kind:     hidden_group_size_z
      - .offset:         138
        .size:           2
        .value_kind:     hidden_remainder_x
      - .offset:         140
        .size:           2
        .value_kind:     hidden_remainder_y
      - .offset:         142
        .size:           2
        .value_kind:     hidden_remainder_z
      - .offset:         160
        .size:           8
        .value_kind:     hidden_global_offset_x
      - .offset:         168
        .size:           8
        .value_kind:     hidden_global_offset_y
      - .offset:         176
        .size:           8
        .value_kind:     hidden_global_offset_z
      - .offset:         184
        .size:           2
        .value_kind:     hidden_grid_dims
      - .offset:         240
        .size:           4
        .value_kind:     hidden_dynamic_lds_size
    .group_segment_fixed_size: 0
    .kernarg_segment_align: 8
    .kernarg_segment_size: 376
    .language:       OpenCL C
    .language_version:
      - 2
      - 0
    .max_flat_workgroup_size: 512
    .name:           _Z10fwd_kernel4Args
    .private_segment_fixed_size: 0
    .sgpr_count:     108
    .sgpr_spill_count: 113
    .symbol:         _Z10fwd_kernel4Args.kd
    .uniform_work_group_size: 1
    .uses_dynamic_stack: false
    .vgpr_count:     256
    .vgpr_spill_count: 0
    .wavefront_size: 64
